# attention stage loop: one static s_setprio 1 for waves 4-7 (reset at loop exit)
# baseline (speedup 1.0000x reference)
.Lattn_pro_done:
	s_waitcnt lgkmcnt(0)
	s_barrier
	v_readfirstlane_b32 s32, v0
	s_nop 3
	s_lshr_b32 s32, s32, 6
	s_cmp_ge_u32 s32, 4
	s_cbranch_scc0 .Lattn_prio_skip
	s_setprio 1
.Lattn_prio_skip:
	s_cmp_lg_u32 s19, 0
	s_cselect_b64 s[28:29], -1, 0
	s_cmp_eq_u32 s19, 0
	s_cbranch_scc1 .LBB0_685

.LBB0_700:
	s_setprio 0
	v_mul_f32_e32 v2, 0x3fb8aa3b, v161
	v_exp_f32_e32 v2, v2
	v_mov_b32_e32 v36, v187
	v_mov_b32_e32 v37, v183
	v_readlane_b32 s4, v254, 60
	v_sub_f32_e32 v2, v165, v2
	v_permlane32_swap_b32_e32 v187, v36
	v_permlane32_swap_b32_e32 v183, v37
	v_add_f32_e32 v2, s4, v2
	v_add_f32_e32 v36, v187, v36
	v_add_f32_e32 v37, v183, v37
	v_cndmask_b32_e64 v2, v2, 1.0, s[38:39]
	v_cndmask_b32_e64 v38, v36, v37, s[38:39]
	v_div_scale_f32 v39, s[4:5], v38, v38, v2
	v_rcp_f32_e32 v40, v39
	v_readlane_b32 s4, v254, 1
	v_cndmask_b32_e64 v44, v64, v80, s[38:39]
	v_cndmask_b32_e64 v45, v63, v79, s[38:39]
	v_fma_f32 v41, -v39, v40, 1.0
	v_fmac_f32_e32 v40, v41, v40
	v_div_scale_f32 v41, vcc, v2, v38, v2
	v_mul_f32_e32 v42, v41, v40
	v_fma_f32 v43, -v39, v42, v41
	v_fmac_f32_e32 v42, v43, v40
	v_fma_f32 v39, -v39, v42, v41
	v_div_fmas_f32 v39, v39, v40, v42
	v_div_fixup_f32 v38, v39, v38, v2
	v_lshlrev_b32_e32 v39, 2, v163
	v_cndmask_b32_e64 v41, v67, v83, s[38:39]
	v_cndmask_b32_e64 v42, v66, v82, s[38:39]
	v_add_u32_e32 v40, s4, v39
	v_mul_f32_e32 v42, v42, v38
	v_mul_f32_e32 v41, v41, v38
	v_cndmask_b32_e64 v43, v65, v81, s[38:39]
	v_cndmask_b32_e64 v46, v62, v78, s[38:39]
	v_cndmask_b32_e64 v47, v61, v77, s[38:39]
	v_cndmask_b32_e64 v48, v60, v76, s[38:39]
	v_cndmask_b32_e64 v49, v59, v75, s[38:39]
	v_cndmask_b32_e64 v50, v58, v74, s[38:39]
	v_cndmask_b32_e64 v51, v57, v73, s[38:39]
	v_cndmask_b32_e64 v84, v56, v72, s[38:39]
	v_cndmask_b32_e64 v85, v55, v71, s[38:39]
	v_cndmask_b32_e64 v86, v54, v70, s[38:39]
	v_cndmask_b32_e64 v87, v53, v69, s[38:39]
	v_cndmask_b32_e64 v88, v52, v68, s[38:39]
	ds_write2st64_b32 v40, v42, v41 offset0:14 offset1:15
	v_cndmask_b32_e64 v41, v35, v19, s[38:39]
	v_cndmask_b32_e64 v42, v34, v18, s[38:39]
	v_mul_f32_e32 v88, v88, v38
	v_mul_f32_e32 v87, v87, v38
	v_mul_f32_e32 v86, v86, v38
	v_mul_f32_e32 v85, v85, v38
	v_mul_f32_e32 v84, v84, v38
	v_mul_f32_e32 v51, v51, v38
	v_mul_f32_e32 v50, v50, v38
	v_mul_f32_e32 v49, v49, v38
	v_mul_f32_e32 v48, v48, v38
	v_mul_f32_e32 v47, v47, v38
	v_mul_f32_e32 v46, v46, v38
	v_mul_f32_e32 v45, v45, v38
	v_mul_f32_e32 v44, v44, v38
	v_mul_f32_e32 v43, v43, v38
	v_mul_f32_e32 v42, v42, v38
	v_cndmask_b32_e64 v36, v37, v36, s[38:39]
	v_mul_f32_e32 v37, v41, v38
	ds_write2st64_b32 v40, v88, v87 offset1:1
	ds_write2st64_b32 v40, v86, v85 offset0:2 offset1:3
	ds_write2st64_b32 v40, v84, v51 offset0:4 offset1:5
	ds_write2st64_b32 v40, v50, v49 offset0:6 offset1:7
	ds_write2st64_b32 v40, v48, v47 offset0:8 offset1:9
	ds_write2st64_b32 v40, v46, v45 offset0:10 offset1:11
	ds_write2st64_b32 v40, v44, v43 offset0:12 offset1:13
	v_cndmask_b32_e64 v43, v33, v17, s[38:39]
	v_cndmask_b32_e64 v44, v32, v16, s[38:39]
	v_cndmask_b32_e64 v45, v31, v15, s[38:39]
	v_cndmask_b32_e64 v46, v30, v14, s[38:39]
	v_cndmask_b32_e64 v47, v29, v13, s[38:39]
	v_cndmask_b32_e64 v48, v28, v12, s[38:39]
	v_cndmask_b32_e64 v49, v27, v11, s[38:39]
	v_cndmask_b32_e64 v50, v26, v10, s[38:39]
	v_cndmask_b32_e64 v51, v25, v9, s[38:39]
	v_cndmask_b32_e64 v84, v24, v8, s[38:39]
	v_cndmask_b32_e64 v85, v23, v7, s[38:39]
	v_cndmask_b32_e64 v86, v22, v6, s[38:39]
	v_cndmask_b32_e64 v87, v21, v5, s[38:39]
	v_cndmask_b32_e64 v88, v20, v4, s[38:39]
	ds_write2st64_b32 v40, v42, v37 offset0:30 offset1:31
	v_div_scale_f32 v37, s[4:5], v36, v36, v2
	v_mul_f32_e32 v88, v88, v38
	v_mul_f32_e32 v87, v87, v38
	v_mul_f32_e32 v86, v86, v38
	v_mul_f32_e32 v85, v85, v38
	v_mul_f32_e32 v84, v84, v38
	v_mul_f32_e32 v51, v51, v38
	v_mul_f32_e32 v50, v50, v38
	v_mul_f32_e32 v49, v49, v38
	v_mul_f32_e32 v48, v48, v38
	v_mul_f32_e32 v47, v47, v38
	v_mul_f32_e32 v46, v46, v38
	v_mul_f32_e32 v45, v45, v38
	v_mul_f32_e32 v44, v44, v38
	v_mul_f32_e32 v43, v43, v38
	v_rcp_f32_e32 v38, v37
	ds_write2st64_b32 v40, v88, v87 offset0:16 offset1:17
	ds_write2st64_b32 v40, v86, v85 offset0:18 offset1:19
	ds_write2st64_b32 v40, v84, v51 offset0:20 offset1:21
	ds_write2st64_b32 v40, v50, v49 offset0:22 offset1:23
	ds_write2st64_b32 v40, v48, v47 offset0:24 offset1:25
	ds_write2st64_b32 v40, v46, v45 offset0:26 offset1:27
	ds_write2st64_b32 v40, v44, v43 offset0:28 offset1:29
	v_fma_f32 v40, -v37, v38, 1.0
	v_fmac_f32_e32 v38, v40, v38
	v_div_scale_f32 v40, vcc, v2, v36, v2
	v_readlane_b32 s4, v254, 2
	v_mul_f32_e32 v41, v40, v38
	s_waitcnt lgkmcnt(0)
	v_add_u32_e32 v84, s4, v39
	s_barrier
	ds_read2st64_b32 v[114:115], v84 offset1:1
	ds_read2st64_b32 v[116:117], v84 offset0:2 offset1:3
	ds_read2st64_b32 v[118:119], v84 offset0:4 offset1:5
	ds_read2st64_b32 v[120:121], v84 offset0:6 offset1:7
	ds_read2st64_b32 v[122:123], v84 offset0:8 offset1:9
	ds_read2st64_b32 v[124:125], v84 offset0:10 offset1:11
	ds_read2st64_b32 v[126:127], v84 offset0:12 offset1:13
	ds_read2st64_b32 v[128:129], v84 offset0:14 offset1:15
	ds_read2st64_b32 v[130:131], v84 offset0:16 offset1:17
	ds_read2st64_b32 v[132:133], v84 offset0:18 offset1:19
	ds_read2st64_b32 v[134:135], v84 offset0:20 offset1:21
	ds_read2st64_b32 v[136:137], v84 offset0:22 offset1:23
	ds_read2st64_b32 v[138:139], v84 offset0:24 offset1:25
	ds_read2st64_b32 v[140:141], v84 offset0:26 offset1:27
	ds_read2st64_b32 v[142:143], v84 offset0:28 offset1:29
	ds_read_b32 v146, v84 offset:7680
	v_fma_f32 v42, -v37, v41, v40
	v_cndmask_b32_e64 v51, v69, v53, s[38:39]
	v_cndmask_b32_e64 v50, v68, v52, s[38:39]
	v_fmac_f32_e32 v41, v42, v38
	v_fma_f32 v37, -v37, v41, v40
	v_div_fmas_f32 v37, v37, v38, v41
	v_div_fixup_f32 v2, v37, v36, v2
	v_cndmask_b32_e64 v43, v77, v61, s[38:39]
	v_cndmask_b32_e64 v42, v76, v60, s[38:39]
	s_waitcnt lgkmcnt(15)
	v_pk_fma_f32 v[60:61], v[50:51], v[2:3], v[114:115] op_sel_hi:[1,0,1] neg_lo:[0,0,1] neg_hi:[0,0,1]
	v_cndmask_b32_e64 v49, v71, v55, s[38:39]
	v_cndmask_b32_e64 v48, v70, v54, s[38:39]
	v_cndmask_b32_e64 v39, v81, v65, s[38:39]
	v_cndmask_b32_e64 v38, v80, v64, s[38:39]
	s_waitcnt lgkmcnt(14)
	v_pk_fma_f32 v[64:65], v[48:49], v[2:3], v[116:117] op_sel_hi:[1,0,1] neg_lo:[0,0,1] neg_hi:[0,0,1]
	v_cndmask_b32_e64 v47, v73, v57, s[38:39]
	v_cndmask_b32_e64 v46, v72, v56, s[38:39]
	v_cndmask_b32_e64 v41, v79, v63, s[38:39]
	v_cndmask_b32_e64 v40, v78, v62, s[38:39]
	s_waitcnt lgkmcnt(13)
	v_pk_fma_f32 v[62:63], v[46:47], v[2:3], v[118:119] op_sel_hi:[1,0,1] neg_lo:[0,0,1] neg_hi:[0,0,1]
	v_cndmask_b32_e64 v45, v75, v59, s[38:39]
	v_cndmask_b32_e64 v44, v74, v58, s[38:39]
	v_cndmask_b32_e64 v37, v83, v67, s[38:39]
	v_cndmask_b32_e64 v36, v82, v66, s[38:39]
	s_waitcnt lgkmcnt(12)
	v_pk_fma_f32 v[66:67], v[44:45], v[2:3], v[120:121] op_sel_hi:[1,0,1] neg_lo:[0,0,1] neg_hi:[0,0,1]
	v_cndmask_b32_e64 v5, v5, v21, s[38:39]
	v_cndmask_b32_e64 v4, v4, v20, s[38:39]
	v_cndmask_b32_e64 v7, v7, v23, s[38:39]
	v_cndmask_b32_e64 v6, v6, v22, s[38:39]
	s_waitcnt lgkmcnt(11)
	v_pk_fma_f32 v[56:57], v[42:43], v[2:3], v[122:123] op_sel_hi:[1,0,1] neg_lo:[0,0,1] neg_hi:[0,0,1]
	v_cndmask_b32_e64 v9, v9, v25, s[38:39]
	v_cndmask_b32_e64 v8, v8, v24, s[38:39]
	v_cndmask_b32_e64 v11, v11, v27, s[38:39]
	v_cndmask_b32_e64 v10, v10, v26, s[38:39]
	s_waitcnt lgkmcnt(10)
	v_pk_fma_f32 v[58:59], v[40:41], v[2:3], v[124:125] op_sel_hi:[1,0,1] neg_lo:[0,0,1] neg_hi:[0,0,1]
	v_cndmask_b32_e64 v13, v13, v29, s[38:39]
	v_cndmask_b32_e64 v12, v12, v28, s[38:39]
	v_cndmask_b32_e64 v15, v15, v31, s[38:39]
	v_cndmask_b32_e64 v14, v14, v30, s[38:39]
	s_waitcnt lgkmcnt(9)
	v_pk_fma_f32 v[46:47], v[38:39], v[2:3], v[126:127] op_sel_hi:[1,0,1] neg_lo:[0,0,1] neg_hi:[0,0,1]
	v_cndmask_b32_e64 v17, v17, v33, s[38:39]
	v_cndmask_b32_e64 v16, v16, v32, s[38:39]
	v_readlane_b32 s4, v253, 63
	v_cndmask_b32_e64 v18, v18, v34, s[38:39]
	s_waitcnt lgkmcnt(8)
	v_pk_fma_f32 v[54:55], v[36:37], v[2:3], v[128:129] op_sel_hi:[1,0,1] neg_lo:[0,0,1] neg_hi:[0,0,1]
	v_readlane_b32 s5, v254, 0
	s_and_b64 vcc, exec, s[4:5]
	s_waitcnt lgkmcnt(7)
	v_pk_fma_f32 v[38:39], v[4:5], v[2:3], v[130:131] op_sel_hi:[1,0,1] neg_lo:[0,0,1] neg_hi:[0,0,1]
	s_waitcnt lgkmcnt(6)
	v_pk_fma_f32 v[40:41], v[6:7], v[2:3], v[132:133] op_sel_hi:[1,0,1] neg_lo:[0,0,1] neg_hi:[0,0,1]
	s_waitcnt lgkmcnt(5)
	v_pk_fma_f32 v[36:37], v[8:9], v[2:3], v[134:135] op_sel_hi:[1,0,1] neg_lo:[0,0,1] neg_hi:[0,0,1]
	s_waitcnt lgkmcnt(4)
	v_pk_fma_f32 v[42:43], v[10:11], v[2:3], v[136:137] op_sel_hi:[1,0,1] neg_lo:[0,0,1] neg_hi:[0,0,1]
	s_waitcnt lgkmcnt(3)
	v_pk_fma_f32 v[48:49], v[12:13], v[2:3], v[138:139] op_sel_hi:[1,0,1] neg_lo:[0,0,1] neg_hi:[0,0,1]
	s_waitcnt lgkmcnt(2)
	v_pk_fma_f32 v[50:51], v[14:15], v[2:3], v[140:141] op_sel_hi:[1,0,1] neg_lo:[0,0,1] neg_hi:[0,0,1]
	s_waitcnt lgkmcnt(1)
	v_pk_fma_f32 v[44:45], v[16:17], v[2:3], v[142:143] op_sel_hi:[1,0,1] neg_lo:[0,0,1] neg_hi:[0,0,1]
	s_waitcnt lgkmcnt(0)
	v_fma_f32 v52, v18, v2, -v146
	s_cbranch_vccnz .LBB0_624
	v_mov_b64_e32 v[4:5], v[20:21]
	v_mov_b64_e32 v[156:157], v[158:159]
	v_mov_b64_e32 v[6:7], v[22:23]
	v_mov_b64_e32 v[8:9], v[24:25]
	v_mov_b64_e32 v[10:11], v[26:27]
	v_mov_b64_e32 v[12:13], v[28:29]
	v_mov_b64_e32 v[14:15], v[30:31]
	v_mov_b64_e32 v[16:17], v[32:33]
	v_mov_b64_e32 v[18:19], v[34:35]
	s_branch .LBB0_625
